# row-norm rebalance + next-row prefetch in both P7 and P11
# speedup vs baseline: 1.0006x; 1.0006x over previous
.LBB0_1262:
	v_readlane_b32 s2, v248, 0
	v_readlane_b32 s3, v248, 1
	s_cmp_lt_i32 s2, 12
	s_cselect_b64 s[2:3], -1, 0
	s_and_b64 s[0:1], s[2:3], s[0:1]
	s_andn2_b64 vcc, exec, s[0:1]
	s_cbranch_vccnz .LBB0_1270
	v_lshl_or_b32 v16, s82, 3, v210
	s_movk_i32 s0, 0x4080
	v_cmp_gt_i32_e32 vcc, s0, v16
	s_and_saveexec_b64 s[0:1], vcc
	s_cbranch_execz .LBB0_1270
	v_lshlrev_b32_e32 v0, 2, v0
	v_and_b32_e32 v17, 0xfc, v0
	v_lshlrev_b32_e32 v18, 2, v17
	v_lshlrev_b32_e32 v22, 1, v17
	v_mbcnt_lo_u32_b32 v17, -1, 0
	v_mbcnt_hi_u32_b32 v17, -1, v17
	v_and_b32_e32 v25, 64, v17
	v_xor_b32_e32 v24, 1, v17
	v_add_u32_e32 v25, 64, v25
	v_cmp_lt_i32_e32 vcc, v24, v25
	v_mov_b32_e32 v19, 0
	v_lshl_add_u64 v[20:21], s[94:95], 0, v[18:19]
	v_cndmask_b32_e32 v24, v17, v24, vcc
	v_lshlrev_b32_e32 v44, 2, v24
	v_xor_b32_e32 v24, 2, v17
	v_cmp_lt_i32_e32 vcc, v24, v25
	s_mov_b64 s[0:1], 0xb3d6400
	v_mov_b32_e32 v23, v19
	v_cndmask_b32_e32 v24, v17, v24, vcc
	v_lshlrev_b32_e32 v45, 2, v24
	v_xor_b32_e32 v24, 4, v17
	v_cmp_lt_i32_e32 vcc, v24, v25
	v_lshl_add_u64 v[20:21], v[20:21], 0, s[0:1]
	v_lshl_add_u64 v[22:23], s[94:95], 0, v[22:23]
	v_cndmask_b32_e32 v24, v17, v24, vcc
	v_lshlrev_b32_e32 v46, 2, v24
	v_xor_b32_e32 v24, 8, v17
	v_cmp_lt_i32_e32 vcc, v24, v25
	s_mov_b64 s[0:1], 0x1f80000
	v_lshl_add_u64 v[22:23], v[22:23], 0, s[0:1]
	v_cndmask_b32_e32 v24, v17, v24, vcc
	v_lshlrev_b32_e32 v47, 2, v24
	v_xor_b32_e32 v24, 16, v17
	v_cmp_lt_i32_e32 vcc, v24, v25
	s_waitcnt lgkmcnt(0)
	s_lshl_b32 s4, s96, 3
	s_mov_b64 s[0:1], 0
	v_cndmask_b32_e32 v24, v17, v24, vcc
	v_lshlrev_b32_e32 v48, 2, v24
	v_xor_b32_e32 v24, 32, v17
	v_cmp_lt_i32_e32 vcc, v24, v25
	s_movk_i32 s5, 0x3fff
	v_mov_b32_e32 v50, 0x3727c5ac
	v_cndmask_b32_e32 v17, v17, v24, vcc
	v_lshlrev_b32_e32 v49, 2, v17
	v_lshl_add_u64 v[24:25], s[92:93], 0, v[18:19]
	s_mov_b32 s6, 0x800000
	s_movk_i32 s7, 0x407f
	v_add_u32_e32 v232, 0xffffff80, v16
	v_and_b32_e32 v233, 0x7f, v232
	v_lshrrev_b32_e32 v234, 7, v232
	v_lshl_add_u32 v233, v234, 11, v233
	v_add_u32_e32 v233, 0x3000, v233
	v_mov_b32_e32 v228, -1
	v_mov_b32_e32 v230, -1
	v_mov_b32_e32 v231, 0x7fffffff
	v_mov_b32_e32 v229, v233
	v_add_u32_e32 v234, 0x4000, v16
	v_add_u32_e32 v235, 0x800, v233
	v_cmp_gt_u32_e32 vcc, 0x100, v232
	s_nop 1
	v_cndmask_b32_e32 v228, v228, v234, vcc
	v_cndmask_b32_e32 v230, v230, v235, vcc
	v_add_u32_e32 v235, 0x3000, v16
	v_cmp_gt_u32_e32 vcc, 0x80, v16
	s_nop 1
	v_cndmask_b32_e32 v228, v228, v235, vcc
	v_cndmask_b32_e32 v229, v229, v234, vcc
	v_mov_b32_e32 v234, v16
	v_mov_b32_e32 v235, 0
	v_lshlrev_b64 v[244:245], 11, v[234:235]
	v_lshl_add_u64 v[244:245], v[22:23], 0, v[244:245]
	global_load_dwordx2 v[236:237], v[244:245], off
	global_load_dwordx2 v[238:239], v[244:245], off offset:512
	global_load_dwordx2 v[240:241], v[244:245], off offset:1024
	global_load_dwordx2 v[242:243], v[244:245], off offset:1536
	global_load_dwordx4 v[0:3], v18, s[90:91]
	global_load_dwordx4 v[4:7], v18, s[90:91] offset:1024
	global_load_dwordx4 v[8:11], v18, s[90:91] offset:2048
	global_load_dwordx4 v[12:15], v18, s[90:91] offset:3072
	s_branch .LBB0_1266
.LBB0_1265:
	s_or_b64 exec, exec, s[2:3]
	v_pk_mul_f32 v[64:65], v[42:43], v[42:43]
	v_pk_mul_f32 v[66:67], v[38:39], v[38:39]
	v_pk_mul_f32 v[60:61], v[40:41], v[40:41]
	v_pk_mul_f32 v[62:63], v[36:37], v[36:37]
	v_mov_b32_e32 v68, v64
	v_mov_b32_e32 v69, v66
	v_mov_b32_e32 v66, v65
	v_pk_add_f32 v[64:65], v[68:69], v[66:67]
	v_mov_b32_e32 v66, v60
	v_mov_b32_e32 v67, v62
	v_pk_mul_f32 v[56:57], v[30:31], v[30:31]
	v_pk_mul_f32 v[58:59], v[34:35], v[34:35]
	v_pk_add_f32 v[64:65], v[66:67], v[64:65]
	v_mov_b32_e32 v62, v61
	v_pk_mul_f32 v[52:53], v[28:29], v[28:29]
	v_pk_mul_f32 v[54:55], v[32:33], v[32:33]
	v_pk_add_f32 v[60:61], v[62:63], v[64:65]
	v_mov_b32_e32 v62, v56
	v_mov_b32_e32 v63, v58
	v_mov_b32_e32 v58, v57
	v_pk_add_f32 v[56:57], v[62:63], v[58:59]
	v_mov_b32_e32 v58, v52
	v_mov_b32_e32 v59, v54
	v_pk_add_f32 v[56:57], v[58:59], v[56:57]
	v_mov_b32_e32 v54, v53
	v_pk_add_f32 v[52:53], v[54:55], v[56:57]
	v_add_f32_e32 v17, v60, v61
	v_add_f32_e32 v17, v53, v17
	v_add_f32_e32 v17, v52, v17
	ds_bpermute_b32 v18, v44, v17
	v_lshl_add_u64 v[52:53], v[24:25], 0, v[26:27]
	v_add_u32_e32 v16, s4, v16
	s_waitcnt lgkmcnt(0)
	v_add_f32_e32 v17, v17, v18
	ds_bpermute_b32 v18, v45, v17
	s_waitcnt lgkmcnt(0)
	v_add_f32_e32 v17, v17, v18
	ds_bpermute_b32 v18, v46, v17
	s_waitcnt lgkmcnt(0)
	v_add_f32_e32 v17, v17, v18
	ds_bpermute_b32 v18, v47, v17
	s_waitcnt lgkmcnt(0)
	v_add_f32_e32 v17, v17, v18
	ds_bpermute_b32 v18, v48, v17
	s_waitcnt lgkmcnt(0)
	v_add_f32_e32 v17, v17, v18
	ds_bpermute_b32 v18, v49, v17
	s_waitcnt lgkmcnt(0)
	v_add_f32_e32 v17, v17, v18
	v_fmamk_f32 v17, v17, 0x3a800000, v50
	v_mul_f32_e32 v18, 0x4b800000, v17
	v_cmp_gt_f32_e32 vcc, s6, v17
	s_nop 1
	v_cndmask_b32_e32 v17, v17, v18, vcc
	v_rsq_f32_e32 v17, v17
	s_nop 0
	v_mul_f32_e32 v18, 0x45800000, v17
	v_cndmask_b32_e32 v18, v17, v18, vcc
	v_pk_mul_f32 v[26:27], v[42:43], v[18:19] op_sel_hi:[1,0]
	v_pk_mul_f32 v[40:41], v[40:41], v[18:19] op_sel_hi:[1,0]
	v_pk_mul_f32 v[54:55], v[36:37], v[18:19] op_sel_hi:[1,0]
	s_waitcnt vmcnt(4)
	v_pk_mul_f32 v[36:37], v[0:1], v[26:27]
	v_pk_mul_f32 v[26:27], v[34:35], v[18:19] op_sel_hi:[1,0]
	v_pk_mul_f32 v[32:33], v[32:33], v[18:19] op_sel_hi:[1,0]
	v_pk_mul_f32 v[42:43], v[38:39], v[18:19] op_sel_hi:[1,0]
	v_pk_mul_f32 v[38:39], v[2:3], v[40:41]
	v_pk_mul_f32 v[34:35], v[10:11], v[32:33]
	v_pk_mul_f32 v[32:33], v[8:9], v[26:27]
	v_pk_mul_f32 v[26:27], v[30:31], v[18:19] op_sel_hi:[1,0]
	v_pk_mul_f32 v[28:29], v[28:29], v[18:19] op_sel_hi:[1,0]
	v_cmp_eq_u32_e32 vcc, v16, v228
	s_nop 1
	v_cndmask_b32_e32 v16, v16, v229, vcc
	v_cmp_eq_u32_e32 vcc, v16, v230
	s_nop 1
	v_cndmask_b32_e32 v16, v16, v231, vcc
	v_cmp_lt_i32_e32 vcc, s7, v16
	global_store_dwordx4 v[52:53], v[36:39], off nt
	v_pk_mul_f32 v[28:29], v[14:15], v[28:29]
	v_pk_mul_f32 v[26:27], v[12:13], v[26:27]
	v_pk_mul_f32 v[38:39], v[6:7], v[54:55]
	v_pk_mul_f32 v[36:37], v[4:5], v[42:43]
	s_or_b64 s[0:1], vcc, s[0:1]
	global_store_dwordx4 v[52:53], v[36:39], off offset:1024 nt
	global_store_dwordx4 v[52:53], v[32:35], off offset:2048 nt
	global_store_dwordx4 v[52:53], v[26:29], off offset:3072 nt
	s_andn2_b64 exec, exec, s[0:1]
	s_cbranch_execz .LBB0_1270

.LBB0_1268:
	s_andn2_saveexec_b64 s[2:3], s[2:3]
	s_cbranch_execz .LBB0_1265
	v_ashrrev_i32_e32 v17, 31, v16
	v_lshlrev_b64 v[26:27], 12, v[16:17]
	s_waitcnt vmcnt(4)
	v_lshlrev_b32_e32 v42, 16, v236
	v_and_b32_e32 v43, 0xffff0000, v236
	v_lshlrev_b32_e32 v40, 16, v237
	v_and_b32_e32 v41, 0xffff0000, v237
	v_lshlrev_b32_e32 v38, 16, v238
	v_and_b32_e32 v39, 0xffff0000, v238
	v_lshlrev_b32_e32 v36, 16, v239
	v_and_b32_e32 v37, 0xffff0000, v239
	v_lshlrev_b32_e32 v34, 16, v240
	v_and_b32_e32 v35, 0xffff0000, v240
	v_lshlrev_b32_e32 v32, 16, v241
	v_and_b32_e32 v33, 0xffff0000, v241
	v_lshlrev_b32_e32 v30, 16, v242
	v_and_b32_e32 v31, 0xffff0000, v242
	v_lshlrev_b32_e32 v28, 16, v243
	v_and_b32_e32 v29, 0xffff0000, v243
	v_add_u32_e32 v234, s4, v16
	v_cmp_eq_u32_e32 vcc, v234, v228
	s_nop 1
	v_cndmask_b32_e32 v234, v234, v229, vcc
	v_cmp_eq_u32_e32 vcc, v234, v230
	s_nop 1
	v_cndmask_b32_e32 v234, v234, v231, vcc
	v_cmp_ge_i32_e32 vcc, s5, v234
	s_and_saveexec_b64 s[98:99], vcc
	s_cbranch_execz .Lp11_nopf
	v_mov_b32_e32 v235, 0
	v_lshlrev_b64 v[244:245], 11, v[234:235]
	v_lshl_add_u64 v[244:245], v[22:23], 0, v[244:245]
	global_load_dwordx2 v[236:237], v[244:245], off
	global_load_dwordx2 v[238:239], v[244:245], off offset:512
	global_load_dwordx2 v[240:241], v[244:245], off offset:1024
	global_load_dwordx2 v[242:243], v[244:245], off offset:1536
.Lp11_nopf:
	s_mov_b64 exec, s[98:99]
	s_branch .LBB0_1265
.LBB0_1270:
	s_endpgm
